# attention item loop: staging-register zero presets and tile-0 -1e30 presets moved into the only paths that read them (66 fewer VALU per item)
# baseline (speedup 1.0000x reference)
.LBB0_1131:
	s_ashr_i32 s44, s58, 6
	s_and_b32 s4, s58, 63
	s_add_i32 s46, s44, s10
	s_lshr_b32 s47, s4, s62
	s_and_b32 s5, s4, s63
	s_add_i32 s4, s11, s46
	s_waitcnt vmcnt(16)
	v_cvt_f32_i32_e32 v0, s4
	s_lshl_b32 s61, s5, 8
	v_readlane_b32 s4, v253, 56
	s_ashr_i32 s45, s44, 31
	v_mul_f32_e32 v0, 0xbe2aaaab, v0
	v_exp_f32_e32 v0, v0
	s_add_i32 s4, s61, s4
	s_lshl_b64 s[12:13], s[44:45], 14
	s_mul_i32 s45, s47, s41
	s_add_u32 s12, s12, s45
	v_or_b32_e32 v138, s4, v150
	s_addc_u32 s13, s13, 0
	v_mul_f32_e32 v2, v0, v152
	v_lshl_add_u64 v[0:1], s[12:13], 0, v[138:139]
	v_lshlrev_b64 v[0:1], 8, v[0:1]
	s_waitcnt vmcnt(8)
	v_mov_b32_e32 v93, v158
	v_lshl_add_u64 v[0:1], v[132:133], 0, v[0:1]
	global_load_dwordx4 v[44:47], v[0:1], off
	global_load_dwordx4 v[40:43], v[0:1], off offset:32
	global_load_dwordx4 v[36:39], v[0:1], off offset:64
	global_load_dwordx4 v[32:35], v[0:1], off offset:96
	global_load_dwordx4 v[28:31], v[0:1], off offset:128
	global_load_dwordx4 v[24:27], v[0:1], off offset:160
	global_load_dwordx4 v[20:23], v[0:1], off offset:192
	global_load_dwordx4 v[16:19], v[0:1], off offset:224
	s_cmpk_gt_u32 s4, 0x7f
	s_mov_b32 s50, s94
	v_mul_f32_e32 v92, 0x3fb8aa3b, v2
	s_cselect_b64 s[48:49], -1, 0
	s_cmpk_lt_u32 s4, 0x80
	s_waitcnt lgkmcnt(0)
	s_barrier
	s_cbranch_scc1 .Lx2_t0skip
	ds_read_b128 v[0:3], v163
	ds_read_b128 v[50:53], v164
	s_mov_b32 s12, 2.0
	s_mov_b32 s13, 0x40400000
	v_cmp_gt_i32_e32 vcc, s67, v93
	s_waitcnt vmcnt(7) lgkmcnt(1)
	v_mfma_f32_32x32x16_bf16 v[0:15], v[0:3], v[44:47], 0
	s_waitcnt vmcnt(6) lgkmcnt(0)
	v_mfma_f32_32x32x16_bf16 v[0:15], v[50:53], v[40:43], v[0:15]
	ds_read_b128 v[50:53], v165
	ds_read_b128 v[54:57], v166
	s_waitcnt vmcnt(5) lgkmcnt(1)
	v_mfma_f32_32x32x16_bf16 v[0:15], v[50:53], v[36:39], v[0:15]
	s_waitcnt vmcnt(4) lgkmcnt(0)
	v_mfma_f32_32x32x16_bf16 v[0:15], v[54:57], v[32:35], v[0:15]
	ds_read_b128 v[50:53], v167
	ds_read_b128 v[54:57], v168
	s_waitcnt vmcnt(3) lgkmcnt(1)
	v_mfma_f32_32x32x16_bf16 v[0:15], v[50:53], v[28:31], v[0:15]
	s_waitcnt vmcnt(2) lgkmcnt(0)
	v_mfma_f32_32x32x16_bf16 v[0:15], v[54:57], v[24:27], v[0:15]
	ds_read_b128 v[50:53], v169
	ds_read_b128 v[54:57], v170
	s_waitcnt vmcnt(1) lgkmcnt(1)
	v_mfma_f32_32x32x16_bf16 v[0:15], v[50:53], v[20:23], v[0:15]
	s_waitcnt vmcnt(0) lgkmcnt(0)
	v_mfma_f32_32x32x16_bf16 v[0:15], v[54:57], v[16:19], v[0:15]
	s_nop 11
	v_pk_fma_f32 v[2:3], v[92:93], s[12:13], v[2:3] op_sel_hi:[0,1,1]
	s_mov_b32 s12, 0x41000000
	s_mov_b32 s13, 0x41100000
	v_pk_fma_f32 v[4:5], v[92:93], s[12:13], v[4:5] op_sel_hi:[0,1,1]
	s_mov_b32 s12, 0x41200000
	s_mov_b32 s13, 0x41300000
	v_pk_fma_f32 v[6:7], v[92:93], s[12:13], v[6:7] op_sel_hi:[0,1,1]
	s_mov_b32 s12, 0x41800000
	s_mov_b32 s13, 0x41880000
	v_pk_fma_f32 v[8:9], v[92:93], s[12:13], v[8:9] op_sel_hi:[0,1,1]
	s_mov_b32 s12, 0x41900000
	s_mov_b32 s13, 0x41980000
	v_pk_fma_f32 v[10:11], v[92:93], s[12:13], v[10:11] op_sel_hi:[0,1,1]
	s_mov_b32 s12, 0x41c00000
	s_mov_b32 s13, 0x41c80000
	v_pk_fma_f32 v[12:13], v[92:93], s[12:13], v[12:13] op_sel_hi:[0,1,1]
	s_mov_b32 s12, 0x41d00000
	s_mov_b32 s13, 0x41d80000
	v_fma_f32 v49, 0, v92, v0
	v_add_f32_e32 v50, v92, v1
	v_pk_fma_f32 v[0:1], v[92:93], s[12:13], v[14:15] op_sel_hi:[0,1,1]
	s_movk_i32 s12, 0x82
	v_cndmask_b32_e32 v85, v175, v49, vcc
	v_cmp_gt_i32_e32 vcc, s12, v93
	s_movk_i32 s12, 0x84
	s_nop 0
	v_cndmask_b32_e32 v100, v175, v50, vcc
	v_cmp_gt_i32_e32 vcc, s12, v93
	s_movk_i32 s12, 0x83
	s_nop 0
	v_cndmask_b32_e32 v101, v175, v3, vcc
	v_cmp_gt_i32_e32 vcc, s12, v93
	s_movk_i32 s12, 0x8a
	s_nop 0
	v_cndmask_b32_e32 v102, v175, v2, vcc
	v_cmp_gt_i32_e32 vcc, s12, v93
	s_movk_i32 s12, 0x89
	s_nop 0
	v_cndmask_b32_e32 v103, v175, v5, vcc
	v_cmp_gt_i32_e32 vcc, s12, v93
	s_movk_i32 s12, 0x8c
	s_nop 0
	v_cndmask_b32_e32 v104, v175, v4, vcc
	v_cmp_gt_i32_e32 vcc, s12, v93
	s_movk_i32 s12, 0x8b
	s_nop 0
	v_cndmask_b32_e32 v105, v175, v7, vcc
	v_cmp_gt_i32_e32 vcc, s12, v93
	s_movk_i32 s12, 0x92
	s_nop 0
	v_cndmask_b32_e32 v106, v175, v6, vcc
	v_cmp_gt_i32_e32 vcc, s12, v93
	s_movk_i32 s12, 0x91
	s_nop 0
	v_cndmask_b32_e32 v107, v175, v9, vcc
	v_cmp_gt_i32_e32 vcc, s12, v93
	s_movk_i32 s12, 0x94
	s_nop 0
	v_cndmask_b32_e32 v108, v175, v8, vcc
	v_cmp_gt_i32_e32 vcc, s12, v93
	s_movk_i32 s12, 0x93
	s_nop 0
	v_cndmask_b32_e32 v109, v175, v11, vcc
	v_cmp_gt_i32_e32 vcc, s12, v93
	s_movk_i32 s12, 0x9a
	s_nop 0
	v_cndmask_b32_e32 v110, v175, v10, vcc
	v_cmp_gt_i32_e32 vcc, s12, v93
	s_movk_i32 s12, 0x99
	s_nop 0
	v_cndmask_b32_e32 v111, v175, v13, vcc
	v_cmp_gt_i32_e32 vcc, s12, v93
	s_movk_i32 s12, 0x9c
	s_nop 0
	v_cndmask_b32_e32 v112, v175, v12, vcc
	v_cmp_gt_i32_e32 vcc, s12, v93
	s_mov_b32 s12, 0xf149f2ca
	s_nop 0
	v_cndmask_b32_e32 v113, v175, v1, vcc
	v_max3_f32 v1, v85, s12, v100
	v_max3_f32 v1, v1, v102, v101
	v_max3_f32 v1, v1, v104, v103
	v_max3_f32 v1, v1, v106, v105
	v_max3_f32 v1, v1, v108, v107
	s_movk_i32 s12, 0x9b
	v_max3_f32 v1, v1, v110, v109
	v_cmp_gt_i32_e32 vcc, s12, v93
	v_max3_f32 v1, v1, v112, v111
	s_nop 0
	v_cndmask_b32_e32 v114, v175, v0, vcc
	v_max3_f32 v84, v1, v114, v113

.LBB0_1196:
	v_pk_mul_f32 v[48:49], v[140:141], v[48:49] op_sel_hi:[0,1]
	v_pk_mul_f32 v[50:51], v[140:141], v[50:51] op_sel_hi:[0,1]
	v_pk_mul_f32 v[32:33], v[140:141], v[32:33] op_sel_hi:[0,1]
	v_pk_mul_f32 v[34:35], v[140:141], v[34:35] op_sel_hi:[0,1]
	v_pk_mul_f32 v[16:17], v[140:141], v[16:17] op_sel_hi:[0,1]
	v_pk_mul_f32 v[18:19], v[140:141], v[18:19] op_sel_hi:[0,1]
	v_pk_mul_f32 v[0:1], v[140:141], v[0:1] op_sel_hi:[0,1]
	v_pk_mul_f32 v[2:3], v[140:141], v[2:3] op_sel_hi:[0,1]
	s_barrier
	ds_write_b128 v162, v[48:51]
	v_pk_mul_f32 v[48:49], v[140:141], v[52:53] op_sel_hi:[0,1]
	v_pk_mul_f32 v[50:51], v[140:141], v[54:55] op_sel_hi:[0,1]
	ds_write_b128 v162, v[32:35] offset:128
	v_pk_mul_f32 v[32:33], v[140:141], v[36:37] op_sel_hi:[0,1]
	v_pk_mul_f32 v[34:35], v[140:141], v[38:39] op_sel_hi:[0,1]
	ds_write_b128 v162, v[16:19] offset:256
	v_pk_mul_f32 v[16:17], v[140:141], v[20:21] op_sel_hi:[0,1]
	v_pk_mul_f32 v[18:19], v[140:141], v[22:23] op_sel_hi:[0,1]
	ds_write_b128 v162, v[0:3] offset:384
	v_pk_mul_f32 v[0:1], v[140:141], v[4:5] op_sel_hi:[0,1]
	v_pk_mul_f32 v[2:3], v[140:141], v[6:7] op_sel_hi:[0,1]
	ds_write_b128 v162, v[48:51] offset:32
	v_pk_mul_f32 v[48:49], v[140:141], v[56:57] op_sel_hi:[0,1]
	v_pk_mul_f32 v[50:51], v[140:141], v[58:59] op_sel_hi:[0,1]
	ds_write_b128 v162, v[32:35] offset:160
	v_pk_mul_f32 v[32:33], v[140:141], v[40:41] op_sel_hi:[0,1]
	v_pk_mul_f32 v[34:35], v[140:141], v[42:43] op_sel_hi:[0,1]
	ds_write_b128 v162, v[16:19] offset:288
	v_pk_mul_f32 v[16:17], v[140:141], v[24:25] op_sel_hi:[0,1]
	v_pk_mul_f32 v[18:19], v[140:141], v[26:27] op_sel_hi:[0,1]
	ds_write_b128 v162, v[0:3] offset:416
	v_pk_mul_f32 v[0:1], v[140:141], v[8:9] op_sel_hi:[0,1]
	v_pk_mul_f32 v[2:3], v[140:141], v[10:11] op_sel_hi:[0,1]
	ds_write_b128 v162, v[48:51] offset:64
	v_pk_mul_f32 v[48:49], v[140:141], v[60:61] op_sel_hi:[0,1]
	v_pk_mul_f32 v[50:51], v[140:141], v[62:63] op_sel_hi:[0,1]
	ds_write_b128 v162, v[32:35] offset:192
	v_pk_mul_f32 v[32:33], v[140:141], v[44:45] op_sel_hi:[0,1]
	v_pk_mul_f32 v[34:35], v[140:141], v[46:47] op_sel_hi:[0,1]
	ds_write_b128 v162, v[16:19] offset:320
	v_pk_mul_f32 v[16:17], v[140:141], v[28:29] op_sel_hi:[0,1]
	v_pk_mul_f32 v[18:19], v[140:141], v[30:31] op_sel_hi:[0,1]
	ds_write_b128 v162, v[0:3] offset:448
	v_pk_mul_f32 v[0:1], v[140:141], v[12:13] op_sel_hi:[0,1]
	v_pk_mul_f32 v[2:3], v[140:141], v[14:15] op_sel_hi:[0,1]
	ds_write_b128 v162, v[48:51] offset:96
	ds_write_b128 v162, v[32:35] offset:224
	ds_write_b128 v162, v[16:19] offset:352
	ds_write_b128 v162, v[0:3] offset:480
	s_and_saveexec_b64 s[12:13], s[42:43]
	ds_write_b32 v160, v144
	s_or_b64 exec, exec, s[12:13]
	s_waitcnt lgkmcnt(0)
	s_add_i32 s58, s58, 1
	s_cmp_lt_i32 s58, s59
	s_cselect_b64 s[94:95], -1, 0
	s_cmp_ge_i32 s58, s59
	s_cbranch_scc1 .Lx2_lastitem
	s_and_b32 s5, s58, 63
	s_and_b32 s14, s5, s63
	s_ashr_i32 s4, s58, 6
	s_lshr_b32 s12, s5, s62
	s_lshl_b32 s5, s14, 8
	s_add_i32 s13, s5, 0xffffff80
	s_ashr_i32 s5, s4, 31
	s_lshl_b64 s[4:5], s[4:5], 14
	s_mul_i32 s12, s12, s41
	s_ashr_i32 s15, s13, 31
	s_add_u32 s12, s13, s12
	s_addc_u32 s13, s15, 0
	s_add_u32 s4, s12, s4
	s_addc_u32 s5, s13, s5
	v_lshl_add_u64 v[0:1], s[4:5], 0, v[128:129]
	v_lshlrev_b64 v[0:1], 8, v[0:1]
	s_cmp_lg_u32 s14, 0
	s_cselect_b64 s[12:13], -1, 0
	s_cmp_eq_u32 s14, 0
	v_lshl_add_u64 v[40:41], v[136:137], 0, v[0:1]
	s_cbranch_scc1 .LBB0_1202
	global_load_dwordx4 v[0:3], v[40:41], off
	s_branch .LBB0_1203
.Lx2_lastitem:
	v_mov_b32_e32 v0, 0
	v_mov_b32_e32 v1, 0
	v_mov_b32_e32 v2, 0
	v_mov_b32_e32 v3, 0
	v_mov_b32_e32 v4, 0
	v_mov_b32_e32 v5, 0
	v_mov_b32_e32 v6, 0
	v_mov_b32_e32 v7, 0
	v_mov_b32_e32 v8, 0
	v_mov_b32_e32 v9, 0
	v_mov_b32_e32 v10, 0
	v_mov_b32_e32 v11, 0
	v_mov_b32_e32 v12, 0
	v_mov_b32_e32 v13, 0
	v_mov_b32_e32 v14, 0
	v_mov_b32_e32 v15, 0
	v_mov_b32_e32 v16, 0
	v_mov_b32_e32 v17, 0
	v_mov_b32_e32 v18, 0
	v_mov_b32_e32 v19, 0
	v_mov_b32_e32 v20, 0
	v_mov_b32_e32 v21, 0
	v_mov_b32_e32 v22, 0
	v_mov_b32_e32 v23, 0
	v_mov_b32_e32 v24, 0
	v_mov_b32_e32 v25, 0
	v_mov_b32_e32 v26, 0
	v_mov_b32_e32 v27, 0
	v_mov_b32_e32 v28, 0
	v_mov_b32_e32 v29, 0
	v_mov_b32_e32 v30, 0
	v_mov_b32_e32 v31, 0
	v_mov_b32_e32 v32, 0
	v_mov_b32_e32 v33, 0
	v_mov_b32_e32 v34, 0
	v_mov_b32_e32 v35, 0
	v_mov_b32_e32 v36, 0
	v_mov_b32_e32 v37, 0
	v_mov_b32_e32 v38, 0
	v_mov_b32_e32 v39, 0
	v_mov_b32_e32 v40, 0
	v_mov_b32_e32 v41, 0
	v_mov_b32_e32 v42, 0
	v_mov_b32_e32 v43, 0
	v_mov_b32_e32 v44, 0
	v_mov_b32_e32 v45, 0
	v_mov_b32_e32 v46, 0
	v_mov_b32_e32 v47, 0
	s_branch .LBB0_1211
.Lx2_t0skip:
	v_mov_b32_e32 v48, 0xf149f2ca
	v_mov_b32_e32 v84, 0xf149f2ca
	v_mov_b32_e32 v85, 0xf149f2ca
	v_mov_b32_e32 v100, 0xf149f2ca
	v_mov_b32_e32 v101, 0xf149f2ca
	v_mov_b32_e32 v102, 0xf149f2ca
	v_mov_b32_e32 v103, 0xf149f2ca
	v_mov_b32_e32 v104, 0xf149f2ca
	v_mov_b32_e32 v105, 0xf149f2ca
	v_mov_b32_e32 v106, 0xf149f2ca
	v_mov_b32_e32 v107, 0xf149f2ca
	v_mov_b32_e32 v108, 0xf149f2ca
	v_mov_b32_e32 v109, 0xf149f2ca
	v_mov_b32_e32 v110, 0xf149f2ca
	v_mov_b32_e32 v111, 0xf149f2ca
	v_mov_b32_e32 v112, 0xf149f2ca
	v_mov_b32_e32 v113, 0xf149f2ca
	v_mov_b32_e32 v114, 0xf149f2ca
	s_branch .LBB0_1133
